# latency-trim stack plus first K-loop iteration of P1/P3/P4 peeled with C=0 MFMAs (accumulator zero-init removed)
# baseline (speedup 1.0000x reference)
.LBB0_175:
	s_mov_b32 s28, s29
	s_ashr_i32 s29, s29, 31
	s_lshl_b64 s[34:35], s[28:29], 20
	s_add_u32 s34, s90, s34
	s_addc_u32 s35, s91, s35
	s_and_b64 s[36:37], s[30:31], exec
	s_mov_b32 s26, s27
	s_cselect_b32 s2, s35, s43
	s_cselect_b32 s29, s34, s42
	s_ashr_i32 s27, s27, 31
	s_lshl_b64 s[36:37], s[26:27], 20
	s_add_u32 s36, s92, s36
	s_addc_u32 s37, s93, s37
	s_and_b64 s[44:45], s[30:31], exec
	s_cselect_b32 s27, s37, s41
	s_cselect_b32 s39, s36, s40
	s_add_u32 s46, s40, 0x100
	s_addc_u32 s47, s41, 0
	s_add_u32 s40, s42, 0x80080
	s_addc_u32 s41, s43, 0
	s_mov_b32 s52, -2
	v_add_u32_e32 v212, 0x18000, v218
	v_add_u32_e32 v213, 0x1c000, v218
	ds_read_b128 v[58:61], v219
	ds_read_b128 v[62:65], v219 offset:1024
	ds_read_b128 v[78:81], v219 offset:2048
	ds_read_b128 v[82:85], v219 offset:3072
	ds_read_b128 v[102:105], v220
	ds_read_b128 v[106:109], v220 offset:1024
	ds_read_b128 v[122:125], v220 offset:2048
	ds_read_b128 v[126:129], v220 offset:3072
	s_add_u32 s42, s40, 0xfff80080
	s_addc_u32 s43, s41, -1
	s_cmp_eq_u32 s52, 28
	s_cselect_b32 s45, s2, s43
	s_cselect_b32 s44, s29, s42
	s_cselect_b32 s43, s27, s47
	s_cselect_b32 s42, s39, s46
	s_add_i32 m0, s49, 0xc000
	ds_read_b128 v[146:149], v221
	ds_read_b128 v[150:153], v221 offset:1024
	ds_read_b128 v[170:173], v221 offset:2048
	ds_read_b128 v[174:177], v221 offset:3072
	ds_read_b128 v[178:181], v221 offset:4096
	ds_read_b128 v[182:185], v221 offset:5120
	ds_read_b128 v[186:189], v221 offset:6144
	ds_read_b128 v[190:193], v221 offset:7168
	global_load_lds_dwordx4 v206, s[40:41]
	s_add_i32 m0, s49, 0xe000
	s_nop 0
	global_load_lds_dwordx4 v208, s[40:41]
	s_waitcnt vmcnt(8) lgkmcnt(0)
	s_barrier
	v_mfma_f32_16x16x32_bf16 v[166:169], v[58:61], v[146:149], 0
	v_mfma_f32_16x16x32_bf16 v[162:165], v[78:81], v[146:149], 0
	v_mfma_f32_16x16x32_bf16 v[142:145], v[58:61], v[170:173], 0
	v_mfma_f32_16x16x32_bf16 v[138:141], v[78:81], v[170:173], 0
	v_mfma_f32_16x16x32_bf16 v[118:121], v[58:61], v[178:181], 0
	v_mfma_f32_16x16x32_bf16 v[114:117], v[78:81], v[178:181], 0
	v_mfma_f32_16x16x32_bf16 v[94:97], v[58:61], v[186:189], 0
	v_mfma_f32_16x16x32_bf16 v[90:93], v[78:81], v[186:189], 0
	v_mfma_f32_16x16x32_bf16 v[166:169], v[62:65], v[150:153], v[166:169]
	v_mfma_f32_16x16x32_bf16 v[162:165], v[82:85], v[150:153], v[162:165]
	v_mfma_f32_16x16x32_bf16 v[142:145], v[62:65], v[174:177], v[142:145]
	v_mfma_f32_16x16x32_bf16 v[138:141], v[82:85], v[174:177], v[138:141]
	v_mfma_f32_16x16x32_bf16 v[118:121], v[62:65], v[182:185], v[118:121]
	v_mfma_f32_16x16x32_bf16 v[114:117], v[82:85], v[182:185], v[114:117]
	v_mfma_f32_16x16x32_bf16 v[94:97], v[62:65], v[190:193], v[94:97]
	v_mfma_f32_16x16x32_bf16 v[90:93], v[82:85], v[190:193], v[90:93]
	v_mfma_f32_16x16x32_bf16 v[158:161], v[102:105], v[146:149], 0
	v_mfma_f32_16x16x32_bf16 v[134:137], v[102:105], v[170:173], 0
	v_mfma_f32_16x16x32_bf16 v[130:133], v[122:125], v[170:173], 0
	v_mfma_f32_16x16x32_bf16 v[110:113], v[102:105], v[178:181], 0
	v_mfma_f32_16x16x32_bf16 v[98:101], v[122:125], v[178:181], 0
	v_mfma_f32_16x16x32_bf16 v[86:89], v[102:105], v[186:189], 0
	v_mfma_f32_16x16x32_bf16 v[74:77], v[122:125], v[186:189], 0
	v_mfma_f32_16x16x32_bf16 v[158:161], v[106:109], v[150:153], v[158:161]
	v_mfma_f32_16x16x32_bf16 v[146:149], v[122:125], v[146:149], 0
	v_mfma_f32_16x16x32_bf16 v[134:137], v[106:109], v[174:177], v[134:137]
	v_mfma_f32_16x16x32_bf16 v[130:133], v[126:129], v[174:177], v[130:133]
	v_mfma_f32_16x16x32_bf16 v[110:113], v[106:109], v[182:185], v[110:113]
	v_mfma_f32_16x16x32_bf16 v[98:101], v[126:129], v[182:185], v[98:101]
	v_mfma_f32_16x16x32_bf16 v[86:89], v[106:109], v[190:193], v[86:89]
	v_mfma_f32_16x16x32_bf16 v[74:77], v[126:129], v[190:193], v[74:77]
	v_mfma_f32_16x16x32_bf16 v[146:149], v[126:129], v[150:153], v[146:149]
	s_barrier
	s_add_i32 m0, s48, 0x10000
	ds_read_b128 v[150:153], v221 offset:16384
	ds_read_b128 v[154:157], v221 offset:17408
	ds_read_b128 v[170:173], v221 offset:18432
	ds_read_b128 v[174:177], v221 offset:19456
	ds_read_b128 v[178:181], v221 offset:20480
	ds_read_b128 v[182:185], v221 offset:21504
	ds_read_b128 v[186:189], v221 offset:22528
	ds_read_b128 v[190:193], v221 offset:23552
	global_load_lds_dwordx4 v198, s[42:43]
	s_add_i32 m0, s48, 0x12000
	s_add_u32 s54, s42, 0x80000
	s_addc_u32 s55, s43, 0
	global_load_lds_dwordx4 v202, s[42:43]
	s_add_i32 m0, s48, 0x14000
	s_nop 0
	global_load_lds_dwordx4 v198, s[54:55]
	s_add_i32 m0, s48, 0x16000
	s_nop 0
	global_load_lds_dwordx4 v202, s[54:55]
	s_mov_b32 m0, s49
	s_nop 0
	global_load_lds_dwordx4 v196, s[44:45]
	s_mov_b32 m0, s50
	s_nop 0
	global_load_lds_dwordx4 v200, s[44:45]
	s_waitcnt vmcnt(8) lgkmcnt(0)
	s_barrier
	v_mfma_f32_16x16x32_bf16 v[70:73], v[58:61], v[150:153], 0
	v_mfma_f32_16x16x32_bf16 v[66:69], v[78:81], v[150:153], 0
	v_mfma_f32_16x16x32_bf16 v[46:49], v[58:61], v[170:173], 0
	v_mfma_f32_16x16x32_bf16 v[42:45], v[78:81], v[170:173], 0
	v_mfma_f32_16x16x32_bf16 v[30:33], v[58:61], v[178:181], 0
	v_mfma_f32_16x16x32_bf16 v[26:29], v[78:81], v[178:181], 0
	v_mfma_f32_16x16x32_bf16 v[14:17], v[58:61], v[186:189], 0
	v_mfma_f32_16x16x32_bf16 v[10:13], v[78:81], v[186:189], 0
	v_mfma_f32_16x16x32_bf16 v[70:73], v[62:65], v[154:157], v[70:73]
	v_mfma_f32_16x16x32_bf16 v[66:69], v[82:85], v[154:157], v[66:69]
	v_mfma_f32_16x16x32_bf16 v[46:49], v[62:65], v[174:177], v[46:49]
	v_mfma_f32_16x16x32_bf16 v[42:45], v[82:85], v[174:177], v[42:45]
	v_mfma_f32_16x16x32_bf16 v[30:33], v[62:65], v[182:185], v[30:33]
	v_mfma_f32_16x16x32_bf16 v[26:29], v[82:85], v[182:185], v[26:29]
	v_mfma_f32_16x16x32_bf16 v[14:17], v[62:65], v[190:193], v[14:17]
	v_mfma_f32_16x16x32_bf16 v[10:13], v[82:85], v[190:193], v[10:13]
	v_mfma_f32_16x16x32_bf16 v[54:57], v[102:105], v[150:153], 0
	v_mfma_f32_16x16x32_bf16 v[50:53], v[122:125], v[150:153], 0
	v_mfma_f32_16x16x32_bf16 v[38:41], v[102:105], v[170:173], 0
	v_mfma_f32_16x16x32_bf16 v[34:37], v[122:125], v[170:173], 0
	v_mfma_f32_16x16x32_bf16 v[22:25], v[102:105], v[178:181], 0
	v_mfma_f32_16x16x32_bf16 v[18:21], v[122:125], v[178:181], 0
	v_mfma_f32_16x16x32_bf16 v[6:9], v[102:105], v[186:189], 0
	v_mfma_f32_16x16x32_bf16 v[2:5], v[122:125], v[186:189], 0
	v_mfma_f32_16x16x32_bf16 v[54:57], v[106:109], v[154:157], v[54:57]
	v_mfma_f32_16x16x32_bf16 v[50:53], v[126:129], v[154:157], v[50:53]
	v_mfma_f32_16x16x32_bf16 v[38:41], v[106:109], v[174:177], v[38:41]
	v_mfma_f32_16x16x32_bf16 v[34:37], v[126:129], v[174:177], v[34:37]
	v_mfma_f32_16x16x32_bf16 v[22:25], v[106:109], v[182:185], v[22:25]
	v_mfma_f32_16x16x32_bf16 v[18:21], v[126:129], v[182:185], v[18:21]
	v_mfma_f32_16x16x32_bf16 v[6:9], v[106:109], v[190:193], v[6:9]
	v_mfma_f32_16x16x32_bf16 v[2:5], v[126:129], v[190:193], v[2:5]
	s_barrier
	ds_read_b128 v[58:61], v212
	ds_read_b128 v[62:65], v212 offset:1024
	ds_read_b128 v[78:81], v212 offset:2048
	ds_read_b128 v[82:85], v212 offset:3072
	ds_read_b128 v[102:105], v213
	ds_read_b128 v[106:109], v213 offset:1024
	ds_read_b128 v[122:125], v213 offset:2048
	ds_read_b128 v[126:129], v213 offset:3072
	s_add_u32 s44, s44, 0x80000
	s_addc_u32 s45, s45, 0
	s_mov_b32 m0, s51
	ds_read_b128 v[150:153], v221 offset:32768
	ds_read_b128 v[154:157], v221 offset:33792
	ds_read_b128 v[170:173], v221 offset:34816
	ds_read_b128 v[174:177], v221 offset:35840
	ds_read_b128 v[178:181], v221 offset:36864
	ds_read_b128 v[182:185], v221 offset:37888
	ds_read_b128 v[186:189], v221 offset:38912
	ds_read_b128 v[190:193], v221 offset:39936
	global_load_lds_dwordx4 v196, s[44:45]
	s_mov_b32 m0, s72
	s_nop 0
	global_load_lds_dwordx4 v200, s[44:45]
	s_waitcnt vmcnt(8) lgkmcnt(0)
	s_barrier
	v_mfma_f32_16x16x32_bf16 v[166:169], v[58:61], v[150:153], v[166:169]
	v_mfma_f32_16x16x32_bf16 v[162:165], v[78:81], v[150:153], v[162:165]
	v_mfma_f32_16x16x32_bf16 v[142:145], v[58:61], v[170:173], v[142:145]
	v_mfma_f32_16x16x32_bf16 v[138:141], v[78:81], v[170:173], v[138:141]
	v_mfma_f32_16x16x32_bf16 v[118:121], v[58:61], v[178:181], v[118:121]
	v_mfma_f32_16x16x32_bf16 v[114:117], v[78:81], v[178:181], v[114:117]
	v_mfma_f32_16x16x32_bf16 v[94:97], v[58:61], v[186:189], v[94:97]
	v_mfma_f32_16x16x32_bf16 v[90:93], v[78:81], v[186:189], v[90:93]
	v_mfma_f32_16x16x32_bf16 v[166:169], v[62:65], v[154:157], v[166:169]
	v_mfma_f32_16x16x32_bf16 v[162:165], v[82:85], v[154:157], v[162:165]
	v_mfma_f32_16x16x32_bf16 v[142:145], v[62:65], v[174:177], v[142:145]
	v_mfma_f32_16x16x32_bf16 v[138:141], v[82:85], v[174:177], v[138:141]
	v_mfma_f32_16x16x32_bf16 v[118:121], v[62:65], v[182:185], v[118:121]
	v_mfma_f32_16x16x32_bf16 v[114:117], v[82:85], v[182:185], v[114:117]
	v_mfma_f32_16x16x32_bf16 v[94:97], v[62:65], v[190:193], v[94:97]
	v_mfma_f32_16x16x32_bf16 v[90:93], v[82:85], v[190:193], v[90:93]
	v_mfma_f32_16x16x32_bf16 v[158:161], v[102:105], v[150:153], v[158:161]
	v_mfma_f32_16x16x32_bf16 v[146:149], v[122:125], v[150:153], v[146:149]
	v_mfma_f32_16x16x32_bf16 v[134:137], v[102:105], v[170:173], v[134:137]
	v_mfma_f32_16x16x32_bf16 v[130:133], v[122:125], v[170:173], v[130:133]
	v_mfma_f32_16x16x32_bf16 v[110:113], v[102:105], v[178:181], v[110:113]
	v_mfma_f32_16x16x32_bf16 v[98:101], v[122:125], v[178:181], v[98:101]
	v_mfma_f32_16x16x32_bf16 v[86:89], v[102:105], v[186:189], v[86:89]
	v_mfma_f32_16x16x32_bf16 v[74:77], v[122:125], v[186:189], v[74:77]
	v_mfma_f32_16x16x32_bf16 v[158:161], v[106:109], v[154:157], v[158:161]
	v_mfma_f32_16x16x32_bf16 v[154:157], v[126:129], v[154:157], v[146:149]
	v_mfma_f32_16x16x32_bf16 v[134:137], v[106:109], v[174:177], v[134:137]
	v_mfma_f32_16x16x32_bf16 v[130:133], v[126:129], v[174:177], v[130:133]
	v_mfma_f32_16x16x32_bf16 v[110:113], v[106:109], v[182:185], v[110:113]
	v_mfma_f32_16x16x32_bf16 v[98:101], v[126:129], v[182:185], v[98:101]
	v_mfma_f32_16x16x32_bf16 v[86:89], v[106:109], v[190:193], v[86:89]
	v_mfma_f32_16x16x32_bf16 v[74:77], v[126:129], v[190:193], v[74:77]
	s_barrier
	s_add_u32 s98, s44, 0xfff80080
	s_addc_u32 s99, s45, -1
	s_add_i32 m0, s48, 0x18000
	ds_read_b128 v[146:149], v221 offset:49152
	ds_read_b128 v[150:153], v221 offset:50176
	ds_read_b128 v[170:173], v221 offset:51200
	ds_read_b128 v[174:177], v221 offset:52224
	ds_read_b128 v[178:181], v221 offset:53248
	ds_read_b128 v[182:185], v221 offset:54272
	ds_read_b128 v[186:189], v221 offset:55296
	ds_read_b128 v[190:193], v221 offset:56320
	s_add_u32 s100, s42, 0x80
	s_addc_u32 s101, s43, 0
	global_load_lds_dwordx4 v198, s[100:101]
	s_add_i32 m0, s48, 0x1a000
	s_add_u32 s42, s42, 0x80080
	s_addc_u32 s43, s43, 0
	global_load_lds_dwordx4 v202, s[100:101]
	s_add_i32 m0, s48, 0x1c000
	s_nop 0
	global_load_lds_dwordx4 v198, s[42:43]
	s_add_i32 m0, s48, 0x1e000
	s_nop 0
	global_load_lds_dwordx4 v202, s[42:43]
	s_mov_b32 m0, s79
	s_nop 0
	global_load_lds_dwordx4 v196, s[98:99]
	s_mov_b32 m0, s80
	s_nop 0
	global_load_lds_dwordx4 v200, s[98:99]
	s_waitcnt vmcnt(8) lgkmcnt(0)
	s_barrier
	v_mfma_f32_16x16x32_bf16 v[70:73], v[58:61], v[146:149], v[70:73]
	v_mfma_f32_16x16x32_bf16 v[66:69], v[78:81], v[146:149], v[66:69]
	v_mfma_f32_16x16x32_bf16 v[46:49], v[58:61], v[170:173], v[46:49]
	v_mfma_f32_16x16x32_bf16 v[42:45], v[78:81], v[170:173], v[42:45]
	v_mfma_f32_16x16x32_bf16 v[30:33], v[58:61], v[178:181], v[30:33]
	v_mfma_f32_16x16x32_bf16 v[26:29], v[78:81], v[178:181], v[26:29]
	v_mfma_f32_16x16x32_bf16 v[14:17], v[58:61], v[186:189], v[14:17]
	v_mfma_f32_16x16x32_bf16 v[10:13], v[78:81], v[186:189], v[10:13]
	v_mfma_f32_16x16x32_bf16 v[70:73], v[62:65], v[150:153], v[70:73]
	v_mfma_f32_16x16x32_bf16 v[66:69], v[82:85], v[150:153], v[66:69]
	v_mfma_f32_16x16x32_bf16 v[46:49], v[62:65], v[174:177], v[46:49]
	v_mfma_f32_16x16x32_bf16 v[42:45], v[82:85], v[174:177], v[42:45]
	v_mfma_f32_16x16x32_bf16 v[30:33], v[62:65], v[182:185], v[30:33]
	v_mfma_f32_16x16x32_bf16 v[26:29], v[82:85], v[182:185], v[26:29]
	v_mfma_f32_16x16x32_bf16 v[14:17], v[62:65], v[190:193], v[14:17]
	v_mfma_f32_16x16x32_bf16 v[10:13], v[82:85], v[190:193], v[10:13]
	v_mfma_f32_16x16x32_bf16 v[54:57], v[102:105], v[146:149], v[54:57]
	v_mfma_f32_16x16x32_bf16 v[50:53], v[122:125], v[146:149], v[50:53]
	v_mfma_f32_16x16x32_bf16 v[38:41], v[102:105], v[170:173], v[38:41]
	v_mfma_f32_16x16x32_bf16 v[34:37], v[122:125], v[170:173], v[34:37]
	v_mfma_f32_16x16x32_bf16 v[22:25], v[102:105], v[178:181], v[22:25]
	v_mfma_f32_16x16x32_bf16 v[18:21], v[122:125], v[178:181], v[18:21]
	v_mfma_f32_16x16x32_bf16 v[6:9], v[102:105], v[186:189], v[6:9]
	v_mfma_f32_16x16x32_bf16 v[2:5], v[122:125], v[186:189], v[2:5]
	v_mfma_f32_16x16x32_bf16 v[54:57], v[106:109], v[150:153], v[54:57]
	v_mfma_f32_16x16x32_bf16 v[50:53], v[126:129], v[150:153], v[50:53]
	v_mfma_f32_16x16x32_bf16 v[38:41], v[106:109], v[174:177], v[38:41]
	v_mfma_f32_16x16x32_bf16 v[34:37], v[126:129], v[174:177], v[34:37]
	v_mfma_f32_16x16x32_bf16 v[22:25], v[106:109], v[182:185], v[22:25]
	v_mfma_f32_16x16x32_bf16 v[18:21], v[126:129], v[182:185], v[18:21]
	v_mfma_f32_16x16x32_bf16 v[6:9], v[106:109], v[190:193], v[6:9]
	v_mfma_f32_16x16x32_bf16 v[2:5], v[126:129], v[190:193], v[2:5]
	s_barrier
	s_add_i32 s52, s52, 2
	s_add_u32 s46, s46, 0x100
	s_addc_u32 s47, s47, 0
	s_add_u32 s40, s40, 0x100
	s_addc_u32 s41, s41, 0

.LBB0_650:
	s_ashr_i32 s15, s14, 31
	s_lshl_b64 s[18:19], s[14:15], 20
	s_add_u32 s18, s92, s18
	s_addc_u32 s19, s93, s19
	s_and_b64 s[20:21], s[16:17], exec
	s_cselect_b32 s15, s19, s29
	s_cselect_b32 s23, s18, s28
	s_ashr_i32 s13, s12, 31
	s_lshl_b64 s[20:21], s[12:13], 20
	s_add_u32 s20, s94, s20
	s_addc_u32 s21, s95, s21
	s_and_b64 s[30:31], s[16:17], exec
	s_cselect_b32 s13, s21, s27
	s_cselect_b32 s43, s20, s26
	s_add_u32 s44, s26, 0x100
	s_addc_u32 s45, s27, 0
	s_add_u32 s26, s28, 0x80080
	s_addc_u32 s27, s29, 0
	s_mov_b32 s46, -2
	s_waitcnt lgkmcnt(0)
	v_add_u32_e32 v192, 0x18000, v195
	v_add_u32_e32 v193, 0x1c000, v195
	ds_read_b128 v[140:143], v197
	ds_read_b128 v[144:147], v197 offset:1024
	ds_read_b128 v[148:151], v197 offset:2048
	ds_read_b128 v[152:155], v197 offset:3072
	ds_read_b128 v[156:159], v198
	ds_read_b128 v[160:163], v198 offset:1024
	ds_read_b128 v[164:167], v198 offset:2048
	ds_read_b128 v[168:171], v198 offset:3072
	s_add_u32 s28, s26, 0xfff80080
	s_addc_u32 s29, s27, -1
	s_cmp_eq_u32 s46, 28
	s_cselect_b32 s31, s15, s29
	s_cselect_b32 s30, s23, s28
	s_cselect_b32 s29, s13, s45
	s_cselect_b32 s28, s43, s44
	s_add_i32 m0, s25, 0xc000
	ds_read_b128 v[172:175], v199
	ds_read_b128 v[176:179], v199 offset:1024
	ds_read_b128 v[180:183], v199 offset:2048
	ds_read_b128 v[184:187], v199 offset:3072
	ds_read_b128 v[188:191], v199 offset:4096
	ds_read_b128 v[202:205], v199 offset:5120
	ds_read_b128 v[206:209], v199 offset:6144
	ds_read_b128 v[210:213], v199 offset:7168
	global_load_lds_dwordx4 v134, s[26:27]
	s_add_i32 m0, s25, 0xe000
	s_nop 0
	global_load_lds_dwordx4 v136, s[26:27]
	s_waitcnt vmcnt(8) lgkmcnt(0)
	s_barrier
	v_mfma_f32_16x16x32_bf16 v[126:129], v[140:143], v[172:175], 0
	v_mfma_f32_16x16x32_bf16 v[122:125], v[148:151], v[172:175], 0
	v_mfma_f32_16x16x32_bf16 v[110:113], v[140:143], v[180:183], 0
	v_mfma_f32_16x16x32_bf16 v[106:109], v[148:151], v[180:183], 0
	v_mfma_f32_16x16x32_bf16 v[94:97], v[140:143], v[188:191], 0
	v_mfma_f32_16x16x32_bf16 v[90:93], v[148:151], v[188:191], 0
	v_mfma_f32_16x16x32_bf16 v[78:81], v[140:143], v[206:209], 0
	v_mfma_f32_16x16x32_bf16 v[74:77], v[148:151], v[206:209], 0
	v_mfma_f32_16x16x32_bf16 v[126:129], v[144:147], v[176:179], v[126:129]
	v_mfma_f32_16x16x32_bf16 v[122:125], v[152:155], v[176:179], v[122:125]
	v_mfma_f32_16x16x32_bf16 v[110:113], v[144:147], v[184:187], v[110:113]
	v_mfma_f32_16x16x32_bf16 v[106:109], v[152:155], v[184:187], v[106:109]
	v_mfma_f32_16x16x32_bf16 v[94:97], v[144:147], v[202:205], v[94:97]
	v_mfma_f32_16x16x32_bf16 v[90:93], v[152:155], v[202:205], v[90:93]
	v_mfma_f32_16x16x32_bf16 v[78:81], v[144:147], v[210:213], v[78:81]
	v_mfma_f32_16x16x32_bf16 v[74:77], v[152:155], v[210:213], v[74:77]
	v_mfma_f32_16x16x32_bf16 v[118:121], v[156:159], v[172:175], 0
	v_mfma_f32_16x16x32_bf16 v[114:117], v[164:167], v[172:175], 0
	v_mfma_f32_16x16x32_bf16 v[102:105], v[156:159], v[180:183], 0
	v_mfma_f32_16x16x32_bf16 v[98:101], v[164:167], v[180:183], 0
	v_mfma_f32_16x16x32_bf16 v[86:89], v[156:159], v[188:191], 0
	v_mfma_f32_16x16x32_bf16 v[82:85], v[164:167], v[188:191], 0
	v_mfma_f32_16x16x32_bf16 v[70:73], v[156:159], v[206:209], 0
	v_mfma_f32_16x16x32_bf16 v[66:69], v[164:167], v[206:209], 0
	v_mfma_f32_16x16x32_bf16 v[118:121], v[160:163], v[176:179], v[118:121]
	v_mfma_f32_16x16x32_bf16 v[114:117], v[168:171], v[176:179], v[114:117]
	v_mfma_f32_16x16x32_bf16 v[102:105], v[160:163], v[184:187], v[102:105]
	v_mfma_f32_16x16x32_bf16 v[98:101], v[168:171], v[184:187], v[98:101]
	v_mfma_f32_16x16x32_bf16 v[86:89], v[160:163], v[202:205], v[86:89]
	v_mfma_f32_16x16x32_bf16 v[82:85], v[168:171], v[202:205], v[82:85]
	v_mfma_f32_16x16x32_bf16 v[70:73], v[160:163], v[210:213], v[70:73]
	v_mfma_f32_16x16x32_bf16 v[66:69], v[168:171], v[210:213], v[66:69]
	s_barrier
	s_add_i32 m0, s3, 0x10000
	ds_read_b128 v[172:175], v199 offset:16384
	ds_read_b128 v[176:179], v199 offset:17408
	ds_read_b128 v[180:183], v199 offset:18432
	ds_read_b128 v[184:187], v199 offset:19456
	ds_read_b128 v[188:191], v199 offset:20480
	ds_read_b128 v[202:205], v199 offset:21504
	ds_read_b128 v[206:209], v199 offset:22528
	ds_read_b128 v[210:213], v199 offset:23552
	global_load_lds_dwordx4 v130, s[28:29]
	s_add_i32 m0, s3, 0x12000
	s_add_u32 s48, s28, 0x80000
	s_addc_u32 s49, s29, 0
	global_load_lds_dwordx4 v132, s[28:29]
	s_add_i32 m0, s3, 0x14000
	s_nop 0
	global_load_lds_dwordx4 v130, s[48:49]
	s_add_i32 m0, s3, 0x16000
	s_nop 0
	global_load_lds_dwordx4 v132, s[48:49]
	s_mov_b32 m0, s25
	s_nop 0
	global_load_lds_dwordx4 v130, s[30:31]
	s_mov_b32 m0, s34
	s_nop 0
	global_load_lds_dwordx4 v132, s[30:31]
	s_waitcnt vmcnt(8) lgkmcnt(0)
	s_barrier
	v_mfma_f32_16x16x32_bf16 v[62:65], v[140:143], v[172:175], 0
	v_mfma_f32_16x16x32_bf16 v[58:61], v[148:151], v[172:175], 0
	v_mfma_f32_16x16x32_bf16 v[46:49], v[140:143], v[180:183], 0
	v_mfma_f32_16x16x32_bf16 v[42:45], v[148:151], v[180:183], 0
	v_mfma_f32_16x16x32_bf16 v[30:33], v[140:143], v[188:191], 0
	v_mfma_f32_16x16x32_bf16 v[26:29], v[148:151], v[188:191], 0
	v_mfma_f32_16x16x32_bf16 v[14:17], v[140:143], v[206:209], 0
	v_mfma_f32_16x16x32_bf16 v[10:13], v[148:151], v[206:209], 0
	v_mfma_f32_16x16x32_bf16 v[62:65], v[144:147], v[176:179], v[62:65]
	v_mfma_f32_16x16x32_bf16 v[58:61], v[152:155], v[176:179], v[58:61]
	v_mfma_f32_16x16x32_bf16 v[46:49], v[144:147], v[184:187], v[46:49]
	v_mfma_f32_16x16x32_bf16 v[42:45], v[152:155], v[184:187], v[42:45]
	v_mfma_f32_16x16x32_bf16 v[30:33], v[144:147], v[202:205], v[30:33]
	v_mfma_f32_16x16x32_bf16 v[26:29], v[152:155], v[202:205], v[26:29]
	v_mfma_f32_16x16x32_bf16 v[14:17], v[144:147], v[210:213], v[14:17]
	v_mfma_f32_16x16x32_bf16 v[10:13], v[152:155], v[210:213], v[10:13]
	v_mfma_f32_16x16x32_bf16 v[54:57], v[156:159], v[172:175], 0
	v_mfma_f32_16x16x32_bf16 v[50:53], v[164:167], v[172:175], 0
	v_mfma_f32_16x16x32_bf16 v[38:41], v[156:159], v[180:183], 0
	v_mfma_f32_16x16x32_bf16 v[34:37], v[164:167], v[180:183], 0
	v_mfma_f32_16x16x32_bf16 v[22:25], v[156:159], v[188:191], 0
	v_mfma_f32_16x16x32_bf16 v[18:21], v[164:167], v[188:191], 0
	v_mfma_f32_16x16x32_bf16 v[6:9], v[156:159], v[206:209], 0
	v_mfma_f32_16x16x32_bf16 v[2:5], v[164:167], v[206:209], 0
	v_mfma_f32_16x16x32_bf16 v[54:57], v[160:163], v[176:179], v[54:57]
	v_mfma_f32_16x16x32_bf16 v[50:53], v[168:171], v[176:179], v[50:53]
	v_mfma_f32_16x16x32_bf16 v[38:41], v[160:163], v[184:187], v[38:41]
	v_mfma_f32_16x16x32_bf16 v[34:37], v[168:171], v[184:187], v[34:37]
	v_mfma_f32_16x16x32_bf16 v[22:25], v[160:163], v[202:205], v[22:25]
	v_mfma_f32_16x16x32_bf16 v[18:21], v[168:171], v[202:205], v[18:21]
	v_mfma_f32_16x16x32_bf16 v[6:9], v[160:163], v[210:213], v[6:9]
	v_mfma_f32_16x16x32_bf16 v[2:5], v[168:171], v[210:213], v[2:5]
	s_barrier
	ds_read_b128 v[140:143], v192
	ds_read_b128 v[144:147], v192 offset:1024
	ds_read_b128 v[148:151], v192 offset:2048
	ds_read_b128 v[152:155], v192 offset:3072
	ds_read_b128 v[156:159], v193
	ds_read_b128 v[160:163], v193 offset:1024
	ds_read_b128 v[164:167], v193 offset:2048
	ds_read_b128 v[168:171], v193 offset:3072
	s_add_u32 s30, s30, 0x80000
	s_addc_u32 s31, s31, 0
	s_mov_b32 m0, s35
	ds_read_b128 v[172:175], v199 offset:32768
	ds_read_b128 v[176:179], v199 offset:33792
	ds_read_b128 v[180:183], v199 offset:34816
	ds_read_b128 v[184:187], v199 offset:35840
	ds_read_b128 v[188:191], v199 offset:36864
	ds_read_b128 v[202:205], v199 offset:37888
	ds_read_b128 v[206:209], v199 offset:38912
	ds_read_b128 v[210:213], v199 offset:39936
	global_load_lds_dwordx4 v130, s[30:31]
	s_mov_b32 m0, s36
	s_nop 0
	global_load_lds_dwordx4 v132, s[30:31]
	s_waitcnt vmcnt(8) lgkmcnt(0)
	s_barrier
	v_mfma_f32_16x16x32_bf16 v[126:129], v[140:143], v[172:175], v[126:129]
	v_mfma_f32_16x16x32_bf16 v[122:125], v[148:151], v[172:175], v[122:125]
	v_mfma_f32_16x16x32_bf16 v[110:113], v[140:143], v[180:183], v[110:113]
	v_mfma_f32_16x16x32_bf16 v[106:109], v[148:151], v[180:183], v[106:109]
	v_mfma_f32_16x16x32_bf16 v[94:97], v[140:143], v[188:191], v[94:97]
	v_mfma_f32_16x16x32_bf16 v[90:93], v[148:151], v[188:191], v[90:93]
	v_mfma_f32_16x16x32_bf16 v[78:81], v[140:143], v[206:209], v[78:81]
	v_mfma_f32_16x16x32_bf16 v[74:77], v[148:151], v[206:209], v[74:77]
	v_mfma_f32_16x16x32_bf16 v[126:129], v[144:147], v[176:179], v[126:129]
	v_mfma_f32_16x16x32_bf16 v[122:125], v[152:155], v[176:179], v[122:125]
	v_mfma_f32_16x16x32_bf16 v[110:113], v[144:147], v[184:187], v[110:113]
	v_mfma_f32_16x16x32_bf16 v[106:109], v[152:155], v[184:187], v[106:109]
	v_mfma_f32_16x16x32_bf16 v[94:97], v[144:147], v[202:205], v[94:97]
	v_mfma_f32_16x16x32_bf16 v[90:93], v[152:155], v[202:205], v[90:93]
	v_mfma_f32_16x16x32_bf16 v[78:81], v[144:147], v[210:213], v[78:81]
	v_mfma_f32_16x16x32_bf16 v[74:77], v[152:155], v[210:213], v[74:77]
	v_mfma_f32_16x16x32_bf16 v[118:121], v[156:159], v[172:175], v[118:121]
	v_mfma_f32_16x16x32_bf16 v[114:117], v[164:167], v[172:175], v[114:117]
	v_mfma_f32_16x16x32_bf16 v[102:105], v[156:159], v[180:183], v[102:105]
	v_mfma_f32_16x16x32_bf16 v[98:101], v[164:167], v[180:183], v[98:101]
	v_mfma_f32_16x16x32_bf16 v[86:89], v[156:159], v[188:191], v[86:89]
	v_mfma_f32_16x16x32_bf16 v[82:85], v[164:167], v[188:191], v[82:85]
	v_mfma_f32_16x16x32_bf16 v[70:73], v[156:159], v[206:209], v[70:73]
	v_mfma_f32_16x16x32_bf16 v[66:69], v[164:167], v[206:209], v[66:69]
	v_mfma_f32_16x16x32_bf16 v[118:121], v[160:163], v[176:179], v[118:121]
	v_mfma_f32_16x16x32_bf16 v[114:117], v[168:171], v[176:179], v[114:117]
	v_mfma_f32_16x16x32_bf16 v[102:105], v[160:163], v[184:187], v[102:105]
	v_mfma_f32_16x16x32_bf16 v[98:101], v[168:171], v[184:187], v[98:101]
	v_mfma_f32_16x16x32_bf16 v[86:89], v[160:163], v[202:205], v[86:89]
	v_mfma_f32_16x16x32_bf16 v[82:85], v[168:171], v[202:205], v[82:85]
	v_mfma_f32_16x16x32_bf16 v[70:73], v[160:163], v[210:213], v[70:73]
	v_mfma_f32_16x16x32_bf16 v[66:69], v[168:171], v[210:213], v[66:69]
	s_barrier
	s_add_u32 s98, s30, 0xfff80080
	s_addc_u32 s99, s31, -1
	s_add_i32 m0, s3, 0x18000
	ds_read_b128 v[172:175], v199 offset:49152
	ds_read_b128 v[176:179], v199 offset:50176
	ds_read_b128 v[180:183], v199 offset:51200
	ds_read_b128 v[184:187], v199 offset:52224
	ds_read_b128 v[188:191], v199 offset:53248
	ds_read_b128 v[202:205], v199 offset:54272
	ds_read_b128 v[206:209], v199 offset:55296
	ds_read_b128 v[210:213], v199 offset:56320
	s_add_u32 s100, s28, 0x80
	s_addc_u32 s101, s29, 0
	global_load_lds_dwordx4 v130, s[100:101]
	s_add_i32 m0, s3, 0x1a000
	s_add_u32 s28, s28, 0x80080
	s_addc_u32 s29, s29, 0
	global_load_lds_dwordx4 v132, s[100:101]
	s_add_i32 m0, s3, 0x1c000
	s_nop 0
	global_load_lds_dwordx4 v130, s[28:29]
	s_add_i32 m0, s3, 0x1e000
	s_nop 0
	global_load_lds_dwordx4 v132, s[28:29]
	s_mov_b32 m0, s38
	s_nop 0
	global_load_lds_dwordx4 v130, s[98:99]
	s_mov_b32 m0, s39
	s_nop 0
	global_load_lds_dwordx4 v132, s[98:99]
	s_waitcnt vmcnt(8) lgkmcnt(0)
	s_barrier
	v_mfma_f32_16x16x32_bf16 v[62:65], v[140:143], v[172:175], v[62:65]
	v_mfma_f32_16x16x32_bf16 v[58:61], v[148:151], v[172:175], v[58:61]
	v_mfma_f32_16x16x32_bf16 v[46:49], v[140:143], v[180:183], v[46:49]
	v_mfma_f32_16x16x32_bf16 v[42:45], v[148:151], v[180:183], v[42:45]
	v_mfma_f32_16x16x32_bf16 v[30:33], v[140:143], v[188:191], v[30:33]
	v_mfma_f32_16x16x32_bf16 v[26:29], v[148:151], v[188:191], v[26:29]
	v_mfma_f32_16x16x32_bf16 v[14:17], v[140:143], v[206:209], v[14:17]
	v_mfma_f32_16x16x32_bf16 v[10:13], v[148:151], v[206:209], v[10:13]
	v_mfma_f32_16x16x32_bf16 v[62:65], v[144:147], v[176:179], v[62:65]
	v_mfma_f32_16x16x32_bf16 v[58:61], v[152:155], v[176:179], v[58:61]
	v_mfma_f32_16x16x32_bf16 v[46:49], v[144:147], v[184:187], v[46:49]
	v_mfma_f32_16x16x32_bf16 v[42:45], v[152:155], v[184:187], v[42:45]
	v_mfma_f32_16x16x32_bf16 v[30:33], v[144:147], v[202:205], v[30:33]
	v_mfma_f32_16x16x32_bf16 v[26:29], v[152:155], v[202:205], v[26:29]
	v_mfma_f32_16x16x32_bf16 v[14:17], v[144:147], v[210:213], v[14:17]
	v_mfma_f32_16x16x32_bf16 v[10:13], v[152:155], v[210:213], v[10:13]
	v_mfma_f32_16x16x32_bf16 v[54:57], v[156:159], v[172:175], v[54:57]
	v_mfma_f32_16x16x32_bf16 v[50:53], v[164:167], v[172:175], v[50:53]
	v_mfma_f32_16x16x32_bf16 v[38:41], v[156:159], v[180:183], v[38:41]
	v_mfma_f32_16x16x32_bf16 v[34:37], v[164:167], v[180:183], v[34:37]
	v_mfma_f32_16x16x32_bf16 v[22:25], v[156:159], v[188:191], v[22:25]
	v_mfma_f32_16x16x32_bf16 v[18:21], v[164:167], v[188:191], v[18:21]
	v_mfma_f32_16x16x32_bf16 v[6:9], v[156:159], v[206:209], v[6:9]
	v_mfma_f32_16x16x32_bf16 v[2:5], v[164:167], v[206:209], v[2:5]
	v_mfma_f32_16x16x32_bf16 v[54:57], v[160:163], v[176:179], v[54:57]
	v_mfma_f32_16x16x32_bf16 v[50:53], v[168:171], v[176:179], v[50:53]
	v_mfma_f32_16x16x32_bf16 v[38:41], v[160:163], v[184:187], v[38:41]
	v_mfma_f32_16x16x32_bf16 v[34:37], v[168:171], v[184:187], v[34:37]
	v_mfma_f32_16x16x32_bf16 v[22:25], v[160:163], v[202:205], v[22:25]
	v_mfma_f32_16x16x32_bf16 v[18:21], v[168:171], v[202:205], v[18:21]
	v_mfma_f32_16x16x32_bf16 v[6:9], v[160:163], v[210:213], v[6:9]
	v_mfma_f32_16x16x32_bf16 v[2:5], v[168:171], v[210:213], v[2:5]
	s_barrier
	s_add_i32 s46, s46, 2
	s_add_u32 s44, s44, 0x100
	s_addc_u32 s45, s45, 0
	s_add_u32 s26, s26, 0x100
	s_addc_u32 s27, s27, 0

.LBB0_807:
	s_mov_b32 s18, s19
	s_ashr_i32 s19, s19, 31
	s_lshl_b64 s[22:23], s[18:19], 20
	s_add_u32 s22, s70, s22
	s_addc_u32 s23, s71, s23
	s_and_b64 s[24:25], s[20:21], exec
	s_mov_b32 s16, s17
	s_cselect_b32 s19, s23, s35
	s_cselect_b32 s51, s22, s34
	s_ashr_i32 s17, s17, 31
	s_lshl_b64 s[24:25], s[16:17], 20
	s_add_u32 s24, s84, s24
	s_addc_u32 s25, s85, s25
	s_and_b64 s[36:37], s[20:21], exec
	s_cselect_b32 s17, s25, s31
	s_cselect_b32 s52, s24, s30
	s_add_u32 s53, s30, 0x100
	s_addc_u32 s54, s31, 0
	s_add_u32 s30, s34, 0x80080
	s_addc_u32 s31, s35, 0
	s_mov_b32 s55, -2
	v_add_u32_e32 v148, 0x18000, v150
	v_add_u32_e32 v149, 0x1c000, v150
	ds_read_b128 v[144:147], v152
	ds_read_b128 v[156:159], v152 offset:1024
	ds_read_b128 v[160:163], v152 offset:2048
	ds_read_b128 v[164:167], v152 offset:3072
	ds_read_b128 v[168:171], v153
	ds_read_b128 v[172:175], v153 offset:1024
	ds_read_b128 v[176:179], v153 offset:2048
	ds_read_b128 v[180:183], v153 offset:3072
	s_add_u32 s34, s30, 0xfff80080
	s_addc_u32 s35, s31, -1
	s_cmp_eq_u32 s55, 28
	s_cselect_b32 s37, s19, s35
	s_cselect_b32 s36, s51, s34
	s_cselect_b32 s35, s17, s54
	s_cselect_b32 s34, s52, s53
	s_add_i32 m0, s27, 0xc000
	ds_read_b128 v[184:187], v154
	ds_read_b128 v[188:191], v154 offset:1024
	ds_read_b128 v[196:199], v154 offset:2048
	ds_read_b128 v[200:203], v154 offset:3072
	ds_read_b128 v[204:207], v154 offset:4096
	ds_read_b128 v[208:211], v154 offset:5120
	ds_read_b128 v[212:215], v154 offset:6144
	ds_read_b128 v[216:219], v154 offset:7168
	global_load_lds_dwordx4 v138, s[30:31]
	s_add_i32 m0, s27, 0xe000
	s_nop 0
	global_load_lds_dwordx4 v140, s[30:31]
	s_waitcnt vmcnt(8) lgkmcnt(0)
	s_barrier
	v_mfma_f32_16x16x32_bf16 v[126:129], v[144:147], v[184:187], 0
	v_mfma_f32_16x16x32_bf16 v[122:125], v[160:163], v[184:187], 0
	v_mfma_f32_16x16x32_bf16 v[110:113], v[144:147], v[196:199], 0
	v_mfma_f32_16x16x32_bf16 v[106:109], v[160:163], v[196:199], 0
	v_mfma_f32_16x16x32_bf16 v[94:97], v[144:147], v[204:207], 0
	v_mfma_f32_16x16x32_bf16 v[90:93], v[160:163], v[204:207], 0
	v_mfma_f32_16x16x32_bf16 v[78:81], v[144:147], v[212:215], 0
	v_mfma_f32_16x16x32_bf16 v[74:77], v[160:163], v[212:215], 0
	v_mfma_f32_16x16x32_bf16 v[126:129], v[156:159], v[188:191], v[126:129]
	v_mfma_f32_16x16x32_bf16 v[122:125], v[164:167], v[188:191], v[122:125]
	v_mfma_f32_16x16x32_bf16 v[110:113], v[156:159], v[200:203], v[110:113]
	v_mfma_f32_16x16x32_bf16 v[106:109], v[164:167], v[200:203], v[106:109]
	v_mfma_f32_16x16x32_bf16 v[94:97], v[156:159], v[208:211], v[94:97]
	v_mfma_f32_16x16x32_bf16 v[90:93], v[164:167], v[208:211], v[90:93]
	v_mfma_f32_16x16x32_bf16 v[78:81], v[156:159], v[216:219], v[78:81]
	v_mfma_f32_16x16x32_bf16 v[74:77], v[164:167], v[216:219], v[74:77]
	v_mfma_f32_16x16x32_bf16 v[118:121], v[168:171], v[184:187], 0
	v_mfma_f32_16x16x32_bf16 v[114:117], v[176:179], v[184:187], 0
	v_mfma_f32_16x16x32_bf16 v[102:105], v[168:171], v[196:199], 0
	v_mfma_f32_16x16x32_bf16 v[98:101], v[176:179], v[196:199], 0
	v_mfma_f32_16x16x32_bf16 v[86:89], v[168:171], v[204:207], 0
	v_mfma_f32_16x16x32_bf16 v[82:85], v[176:179], v[204:207], 0
	v_mfma_f32_16x16x32_bf16 v[70:73], v[168:171], v[212:215], 0
	v_mfma_f32_16x16x32_bf16 v[66:69], v[176:179], v[212:215], 0
	v_mfma_f32_16x16x32_bf16 v[118:121], v[172:175], v[188:191], v[118:121]
	v_mfma_f32_16x16x32_bf16 v[114:117], v[180:183], v[188:191], v[114:117]
	v_mfma_f32_16x16x32_bf16 v[102:105], v[172:175], v[200:203], v[102:105]
	v_mfma_f32_16x16x32_bf16 v[98:101], v[180:183], v[200:203], v[98:101]
	v_mfma_f32_16x16x32_bf16 v[86:89], v[172:175], v[208:211], v[86:89]
	v_mfma_f32_16x16x32_bf16 v[82:85], v[180:183], v[208:211], v[82:85]
	v_mfma_f32_16x16x32_bf16 v[70:73], v[172:175], v[216:219], v[70:73]
	v_mfma_f32_16x16x32_bf16 v[66:69], v[180:183], v[216:219], v[66:69]
	s_barrier
	s_add_i32 m0, s38, 0x10000
	ds_read_b128 v[184:187], v154 offset:16384
	ds_read_b128 v[188:191], v154 offset:17408
	ds_read_b128 v[196:199], v154 offset:18432
	ds_read_b128 v[200:203], v154 offset:19456
	ds_read_b128 v[204:207], v154 offset:20480
	ds_read_b128 v[208:211], v154 offset:21504
	ds_read_b128 v[212:215], v154 offset:22528
	ds_read_b128 v[216:219], v154 offset:23552
	global_load_lds_dwordx4 v132, s[34:35]
	s_add_i32 m0, s38, 0x12000
	s_add_u32 s56, s34, 0x80000
	s_addc_u32 s57, s35, 0
	global_load_lds_dwordx4 v136, s[34:35]
	s_add_i32 m0, s38, 0x14000
	s_nop 0
	global_load_lds_dwordx4 v132, s[56:57]
	s_add_i32 m0, s38, 0x16000
	s_nop 0
	global_load_lds_dwordx4 v136, s[56:57]
	s_mov_b32 m0, s27
	s_nop 0
	global_load_lds_dwordx4 v130, s[36:37]
	s_mov_b32 m0, s29
	s_nop 0
	global_load_lds_dwordx4 v134, s[36:37]
	s_waitcnt vmcnt(8) lgkmcnt(0)
	s_barrier
	v_mfma_f32_16x16x32_bf16 v[62:65], v[144:147], v[184:187], 0
	v_mfma_f32_16x16x32_bf16 v[58:61], v[160:163], v[184:187], 0
	v_mfma_f32_16x16x32_bf16 v[46:49], v[144:147], v[196:199], 0
	v_mfma_f32_16x16x32_bf16 v[42:45], v[160:163], v[196:199], 0
	v_mfma_f32_16x16x32_bf16 v[30:33], v[144:147], v[204:207], 0
	v_mfma_f32_16x16x32_bf16 v[26:29], v[160:163], v[204:207], 0
	v_mfma_f32_16x16x32_bf16 v[14:17], v[144:147], v[212:215], 0
	v_mfma_f32_16x16x32_bf16 v[10:13], v[160:163], v[212:215], 0
	v_mfma_f32_16x16x32_bf16 v[62:65], v[156:159], v[188:191], v[62:65]
	v_mfma_f32_16x16x32_bf16 v[58:61], v[164:167], v[188:191], v[58:61]
	v_mfma_f32_16x16x32_bf16 v[46:49], v[156:159], v[200:203], v[46:49]
	v_mfma_f32_16x16x32_bf16 v[42:45], v[164:167], v[200:203], v[42:45]
	v_mfma_f32_16x16x32_bf16 v[30:33], v[156:159], v[208:211], v[30:33]
	v_mfma_f32_16x16x32_bf16 v[26:29], v[164:167], v[208:211], v[26:29]
	v_mfma_f32_16x16x32_bf16 v[14:17], v[156:159], v[216:219], v[14:17]
	v_mfma_f32_16x16x32_bf16 v[10:13], v[164:167], v[216:219], v[10:13]
	v_mfma_f32_16x16x32_bf16 v[54:57], v[168:171], v[184:187], 0
	v_mfma_f32_16x16x32_bf16 v[50:53], v[176:179], v[184:187], 0
	v_mfma_f32_16x16x32_bf16 v[38:41], v[168:171], v[196:199], 0
	v_mfma_f32_16x16x32_bf16 v[34:37], v[176:179], v[196:199], 0
	v_mfma_f32_16x16x32_bf16 v[22:25], v[168:171], v[204:207], 0
	v_mfma_f32_16x16x32_bf16 v[18:21], v[176:179], v[204:207], 0
	v_mfma_f32_16x16x32_bf16 v[6:9], v[168:171], v[212:215], 0
	v_mfma_f32_16x16x32_bf16 v[2:5], v[176:179], v[212:215], 0
	v_mfma_f32_16x16x32_bf16 v[54:57], v[172:175], v[188:191], v[54:57]
	v_mfma_f32_16x16x32_bf16 v[50:53], v[180:183], v[188:191], v[50:53]
	v_mfma_f32_16x16x32_bf16 v[38:41], v[172:175], v[200:203], v[38:41]
	v_mfma_f32_16x16x32_bf16 v[34:37], v[180:183], v[200:203], v[34:37]
	v_mfma_f32_16x16x32_bf16 v[22:25], v[172:175], v[208:211], v[22:25]
	v_mfma_f32_16x16x32_bf16 v[18:21], v[180:183], v[208:211], v[18:21]
	v_mfma_f32_16x16x32_bf16 v[6:9], v[172:175], v[216:219], v[6:9]
	v_mfma_f32_16x16x32_bf16 v[2:5], v[180:183], v[216:219], v[2:5]
	s_barrier
	ds_read_b128 v[144:147], v148
	ds_read_b128 v[156:159], v148 offset:1024
	ds_read_b128 v[160:163], v148 offset:2048
	ds_read_b128 v[164:167], v148 offset:3072
	ds_read_b128 v[168:171], v149
	ds_read_b128 v[172:175], v149 offset:1024
	ds_read_b128 v[176:179], v149 offset:2048
	ds_read_b128 v[180:183], v149 offset:3072
	s_add_u32 s36, s36, 0x80000
	s_addc_u32 s37, s37, 0
	s_mov_b32 m0, s39
	ds_read_b128 v[184:187], v154 offset:32768
	ds_read_b128 v[188:191], v154 offset:33792
	ds_read_b128 v[196:199], v154 offset:34816
	ds_read_b128 v[200:203], v154 offset:35840
	ds_read_b128 v[204:207], v154 offset:36864
	ds_read_b128 v[208:211], v154 offset:37888
	ds_read_b128 v[212:215], v154 offset:38912
	ds_read_b128 v[216:219], v154 offset:39936
	global_load_lds_dwordx4 v130, s[36:37]
	s_mov_b32 m0, s40
	s_nop 0
	global_load_lds_dwordx4 v134, s[36:37]
	s_waitcnt vmcnt(8) lgkmcnt(0)
	s_barrier
	v_mfma_f32_16x16x32_bf16 v[126:129], v[144:147], v[184:187], v[126:129]
	v_mfma_f32_16x16x32_bf16 v[122:125], v[160:163], v[184:187], v[122:125]
	v_mfma_f32_16x16x32_bf16 v[110:113], v[144:147], v[196:199], v[110:113]
	v_mfma_f32_16x16x32_bf16 v[106:109], v[160:163], v[196:199], v[106:109]
	v_mfma_f32_16x16x32_bf16 v[94:97], v[144:147], v[204:207], v[94:97]
	v_mfma_f32_16x16x32_bf16 v[90:93], v[160:163], v[204:207], v[90:93]
	v_mfma_f32_16x16x32_bf16 v[78:81], v[144:147], v[212:215], v[78:81]
	v_mfma_f32_16x16x32_bf16 v[74:77], v[160:163], v[212:215], v[74:77]
	v_mfma_f32_16x16x32_bf16 v[126:129], v[156:159], v[188:191], v[126:129]
	v_mfma_f32_16x16x32_bf16 v[122:125], v[164:167], v[188:191], v[122:125]
	v_mfma_f32_16x16x32_bf16 v[110:113], v[156:159], v[200:203], v[110:113]
	v_mfma_f32_16x16x32_bf16 v[106:109], v[164:167], v[200:203], v[106:109]
	v_mfma_f32_16x16x32_bf16 v[94:97], v[156:159], v[208:211], v[94:97]
	v_mfma_f32_16x16x32_bf16 v[90:93], v[164:167], v[208:211], v[90:93]
	v_mfma_f32_16x16x32_bf16 v[78:81], v[156:159], v[216:219], v[78:81]
	v_mfma_f32_16x16x32_bf16 v[74:77], v[164:167], v[216:219], v[74:77]
	v_mfma_f32_16x16x32_bf16 v[118:121], v[168:171], v[184:187], v[118:121]
	v_mfma_f32_16x16x32_bf16 v[114:117], v[176:179], v[184:187], v[114:117]
	v_mfma_f32_16x16x32_bf16 v[102:105], v[168:171], v[196:199], v[102:105]
	v_mfma_f32_16x16x32_bf16 v[98:101], v[176:179], v[196:199], v[98:101]
	v_mfma_f32_16x16x32_bf16 v[86:89], v[168:171], v[204:207], v[86:89]
	v_mfma_f32_16x16x32_bf16 v[82:85], v[176:179], v[204:207], v[82:85]
	v_mfma_f32_16x16x32_bf16 v[70:73], v[168:171], v[212:215], v[70:73]
	v_mfma_f32_16x16x32_bf16 v[66:69], v[176:179], v[212:215], v[66:69]
	v_mfma_f32_16x16x32_bf16 v[118:121], v[172:175], v[188:191], v[118:121]
	v_mfma_f32_16x16x32_bf16 v[114:117], v[180:183], v[188:191], v[114:117]
	v_mfma_f32_16x16x32_bf16 v[102:105], v[172:175], v[200:203], v[102:105]
	v_mfma_f32_16x16x32_bf16 v[98:101], v[180:183], v[200:203], v[98:101]
	v_mfma_f32_16x16x32_bf16 v[86:89], v[172:175], v[208:211], v[86:89]
	v_mfma_f32_16x16x32_bf16 v[82:85], v[180:183], v[208:211], v[82:85]
	v_mfma_f32_16x16x32_bf16 v[70:73], v[172:175], v[216:219], v[70:73]
	v_mfma_f32_16x16x32_bf16 v[66:69], v[180:183], v[216:219], v[66:69]
	s_barrier
	s_add_u32 s98, s36, 0xfff80080
	s_addc_u32 s99, s37, -1
	s_add_i32 m0, s38, 0x18000
	ds_read_b128 v[184:187], v154 offset:49152
	ds_read_b128 v[188:191], v154 offset:50176
	ds_read_b128 v[196:199], v154 offset:51200
	ds_read_b128 v[200:203], v154 offset:52224
	ds_read_b128 v[204:207], v154 offset:53248
	ds_read_b128 v[208:211], v154 offset:54272
	ds_read_b128 v[212:215], v154 offset:55296
	ds_read_b128 v[216:219], v154 offset:56320
	s_add_u32 s100, s34, 0x80
	s_addc_u32 s101, s35, 0
	global_load_lds_dwordx4 v132, s[100:101]
	s_add_i32 m0, s38, 0x1a000
	s_add_u32 s34, s34, 0x80080
	s_addc_u32 s35, s35, 0
	global_load_lds_dwordx4 v136, s[100:101]
	s_add_i32 m0, s38, 0x1c000
	s_nop 0
	global_load_lds_dwordx4 v132, s[34:35]
	s_add_i32 m0, s38, 0x1e000
	s_nop 0
	global_load_lds_dwordx4 v136, s[34:35]
	s_mov_b32 m0, s42
	s_nop 0
	global_load_lds_dwordx4 v130, s[98:99]
	s_mov_b32 m0, s43
	s_nop 0
	global_load_lds_dwordx4 v134, s[98:99]
	s_waitcnt vmcnt(8) lgkmcnt(0)
	s_barrier
	v_mfma_f32_16x16x32_bf16 v[62:65], v[144:147], v[184:187], v[62:65]
	v_mfma_f32_16x16x32_bf16 v[58:61], v[160:163], v[184:187], v[58:61]
	v_mfma_f32_16x16x32_bf16 v[46:49], v[144:147], v[196:199], v[46:49]
	v_mfma_f32_16x16x32_bf16 v[42:45], v[160:163], v[196:199], v[42:45]
	v_mfma_f32_16x16x32_bf16 v[30:33], v[144:147], v[204:207], v[30:33]
	v_mfma_f32_16x16x32_bf16 v[26:29], v[160:163], v[204:207], v[26:29]
	v_mfma_f32_16x16x32_bf16 v[14:17], v[144:147], v[212:215], v[14:17]
	v_mfma_f32_16x16x32_bf16 v[10:13], v[160:163], v[212:215], v[10:13]
	v_mfma_f32_16x16x32_bf16 v[62:65], v[156:159], v[188:191], v[62:65]
	v_mfma_f32_16x16x32_bf16 v[58:61], v[164:167], v[188:191], v[58:61]
	v_mfma_f32_16x16x32_bf16 v[46:49], v[156:159], v[200:203], v[46:49]
	v_mfma_f32_16x16x32_bf16 v[42:45], v[164:167], v[200:203], v[42:45]
	v_mfma_f32_16x16x32_bf16 v[30:33], v[156:159], v[208:211], v[30:33]
	v_mfma_f32_16x16x32_bf16 v[26:29], v[164:167], v[208:211], v[26:29]
	v_mfma_f32_16x16x32_bf16 v[14:17], v[156:159], v[216:219], v[14:17]
	v_mfma_f32_16x16x32_bf16 v[10:13], v[164:167], v[216:219], v[10:13]
	v_mfma_f32_16x16x32_bf16 v[54:57], v[168:171], v[184:187], v[54:57]
	v_mfma_f32_16x16x32_bf16 v[50:53], v[176:179], v[184:187], v[50:53]
	v_mfma_f32_16x16x32_bf16 v[38:41], v[168:171], v[196:199], v[38:41]
	v_mfma_f32_16x16x32_bf16 v[34:37], v[176:179], v[196:199], v[34:37]
	v_mfma_f32_16x16x32_bf16 v[22:25], v[168:171], v[204:207], v[22:25]
	v_mfma_f32_16x16x32_bf16 v[18:21], v[176:179], v[204:207], v[18:21]
	v_mfma_f32_16x16x32_bf16 v[6:9], v[168:171], v[212:215], v[6:9]
	v_mfma_f32_16x16x32_bf16 v[2:5], v[176:179], v[212:215], v[2:5]
	v_mfma_f32_16x16x32_bf16 v[54:57], v[172:175], v[188:191], v[54:57]
	v_mfma_f32_16x16x32_bf16 v[50:53], v[180:183], v[188:191], v[50:53]
	v_mfma_f32_16x16x32_bf16 v[38:41], v[172:175], v[200:203], v[38:41]
	v_mfma_f32_16x16x32_bf16 v[34:37], v[180:183], v[200:203], v[34:37]
	v_mfma_f32_16x16x32_bf16 v[22:25], v[172:175], v[208:211], v[22:25]
	v_mfma_f32_16x16x32_bf16 v[18:21], v[180:183], v[208:211], v[18:21]
	v_mfma_f32_16x16x32_bf16 v[6:9], v[172:175], v[216:219], v[6:9]
	v_mfma_f32_16x16x32_bf16 v[2:5], v[180:183], v[216:219], v[2:5]
	s_barrier
	s_add_i32 s55, s55, 2
	s_add_u32 s53, s53, 0x100
	s_addc_u32 s54, s54, 0
	s_add_u32 s30, s30, 0x100
	s_addc_u32 s31, s31, 0
